# v6 + hyena: MFMA waves L2-prefetch the next channel's v rows and taps at the ORDER-1 segment start
# baseline (speedup 1.0000x reference)
.LBB0_706:
	s_cmpk_ge_i32 s90, 0x100
	s_cbranch_scc1 .Lhy_npf_skip_0
	v_and_b32_e32 v253, 3, v0
	v_bfe_u32 v254, v0, 5, 3
	v_lshlrev_b32_e32 v253, 7, v253
	s_add_i32 s98, s90, 0x100
	s_mov_b32 s99, 0
	v_lshl_or_b32 v253, v254, 9, v253
	v_lshl_add_u64 v[254:255], v[160:161], 0, s[98:99]
	v_lshlrev_b64 v[254:255], 12, v[254:255]
	v_lshl_add_u64 v[254:255], s[4:5], 0, v[254:255]
	v_or_b32_e32 v254, v254, v253
	global_load_dword v250, v[254:255], off
	s_lshl_b32 s98, s98, 14
	s_add_u32 s98, s98, 0xf0600000
	s_addc_u32 s99, 0, -1
	s_add_u32 s98, s4, s98
	s_addc_u32 s99, s5, s99
	v_and_b32_e32 v253, 0x7f, v0
	v_lshlrev_b32_e32 v253, 7, v253
	global_load_dword v250, v253, s[98:99]
